# v41 + sc1 (L1 bypass) on the K/V tile LDS-DMA loads of the diff-attention loop
# baseline (speedup 1.0000x reference)
.LBB0_1599:
	s_cmp_ge_u32 s68, s59
	s_cbranch_scc1 .Lyka_xtail
	v_add_u32_e32 v0, s72, v208
	ds_read_b128 v[80:83], v0
	ds_read_b128 v[84:87], v0 offset:512
	ds_read_b128 v[6:9], v0 offset:2048
	ds_read_b128 v[112:115], v0 offset:2560
	ds_read_b128 v[10:13], v0 offset:4096
	ds_read_b128 v[116:119], v0 offset:4608
	ds_read_b128 v[2:5], v0 offset:6144
	ds_read_b128 v[120:123], v0 offset:6656
	s_and_b64 vcc, exec, s[8:9]
	s_cbranch_vccnz .LBB0_1608
	s_add_i32 s3, s69, s66
	s_mov_b32 m0, s3
	v_lshl_add_u64 v[14:15], v[168:169], 0, s[28:29]
	global_load_lds_dwordx4 v[168:169], off sc1
	s_add_i32 m0, s3, 0x2000
	s_nop 0
	global_load_lds_dwordx4 v[14:15], off sc1
	v_lshl_add_u64 v[14:15], v[168:169], 0, s[40:41]
	s_add_i32 m0, s3, 0x4000
	s_nop 0
	global_load_lds_dwordx4 v[14:15], off sc1
	v_lshl_add_u64 v[14:15], v[168:169], 0, s[80:81]
	s_add_i32 m0, s3, 0x6000
	s_nop 0
	global_load_lds_dwordx4 v[14:15], off sc1

.Lyka_ypre:
	s_cmp_eq_u32 s65, 0
	s_cbranch_scc1 .Lyka_pre
	s_mov_b32 s5, m0
	s_add_i32 s3, s66, 0x10000
	s_mov_b32 m0, s3
	v_lshl_add_u64 v[2:3], v[168:169], 0, s[28:29]
	global_load_lds_dwordx4 v[168:169], off sc1
	s_add_i32 s4, s3, 0x2000
	s_mov_b32 m0, s4
	v_lshl_add_u64 v[4:5], v[168:169], 0, s[40:41]
	global_load_lds_dwordx4 v[2:3], off sc1
	s_add_i32 s4, s3, 0x4000
	s_mov_b32 m0, s4
	v_lshl_add_u64 v[2:3], v[168:169], 0, s[80:81]
	global_load_lds_dwordx4 v[4:5], off sc1
	s_addk_i32 s3, 0x6000
	s_mov_b32 m0, s3
	s_nop 0
	global_load_lds_dwordx4 v[2:3], off sc1
	s_mov_b32 m0, s5

.Lyka_ytop:
	s_cmp_ge_u32 s68, s59
	s_cbranch_scc1 .Lyka_ytail
	v_add_u32_e32 v0, s72, v208
	ds_read_b128 v[80:83], v0
	ds_read_b128 v[84:87], v0 offset:512
	ds_read_b128 v[6:9], v0 offset:2048
	ds_read_b128 v[112:115], v0 offset:2560
	ds_read_b128 v[10:13], v0 offset:4096
	ds_read_b128 v[116:119], v0 offset:4608
	ds_read_b128 v[2:5], v0 offset:6144
	ds_read_b128 v[120:123], v0 offset:6656
	v_add_f32_e32 v14, 0, v170
	v_add_f32_e32 v15, 0, v171
	v_cvt_pk_bf16_f32 v124, v170, v172
	v_add_f32_e32 v14, v172, v14
	v_add_f32_e32 v15, v173, v15
	v_cvt_pk_bf16_f32 v125, v174, v176
	v_add_f32_e32 v14, v174, v14
	v_add_f32_e32 v15, v175, v15
	v_cvt_pk_bf16_f32 v126, v178, v180
	v_add_f32_e32 v14, v176, v14
	v_add_f32_e32 v15, v177, v15
	v_cvt_pk_bf16_f32 v127, v182, v184
	v_add_f32_e32 v14, v178, v14
	v_add_f32_e32 v15, v179, v15
	v_cvt_pk_bf16_f32 v128, v186, v188
	v_add_f32_e32 v14, v180, v14
	v_add_f32_e32 v15, v181, v15
	v_cvt_pk_bf16_f32 v129, v190, v192
	v_add_f32_e32 v14, v182, v14
	v_add_f32_e32 v15, v183, v15
	v_cvt_pk_bf16_f32 v130, v194, v196
	v_add_f32_e32 v14, v184, v14
	v_add_f32_e32 v15, v185, v15
	v_cvt_pk_bf16_f32 v131, v198, v200
	v_add_f32_e32 v14, v186, v14
	v_add_f32_e32 v15, v187, v15
	v_cvt_pk_bf16_f32 v132, v171, v173
	v_add_f32_e32 v14, v188, v14
	v_add_f32_e32 v15, v189, v15
	v_cvt_pk_bf16_f32 v133, v175, v177
	v_add_f32_e32 v14, v190, v14
	v_add_f32_e32 v15, v191, v15
	v_cvt_pk_bf16_f32 v134, v179, v181
	v_add_f32_e32 v14, v192, v14
	v_add_f32_e32 v15, v193, v15
	v_cvt_pk_bf16_f32 v135, v183, v185
	v_add_f32_e32 v14, v194, v14
	v_add_f32_e32 v15, v195, v15
	v_cvt_pk_bf16_f32 v136, v187, v189
	v_add_f32_e32 v14, v196, v14
	v_add_f32_e32 v15, v197, v15
	v_cvt_pk_bf16_f32 v137, v191, v193
	v_add_f32_e32 v14, v198, v14
	v_add_f32_e32 v15, v199, v15
	v_cvt_pk_bf16_f32 v138, v195, v197
	v_add_f32_e32 v14, v200, v14
	v_add_f32_e32 v15, v201, v15
	v_cvt_pk_bf16_f32 v139, v199, v201
	v_add_f32_e32 v0, v14, v15
	s_waitcnt lgkmcnt(7)
	v_mfma_f32_32x32x16_bf16 v[96:111], v[80:83], v[144:147], 0
	v_add_u32_e32 v14, s71, v209
	s_waitcnt lgkmcnt(6)
	v_mfma_f32_32x32x16_bf16 v[80:95], v[84:87], v[144:147], 0
	s_waitcnt lgkmcnt(4)
	v_mfma_f32_32x32x16_bf16 v[80:95], v[112:115], v[148:151], v[80:95]
	v_mfma_f32_32x32x16_bf16 v[96:111], v[6:9], v[148:151], v[96:111]
	s_waitcnt lgkmcnt(2)
	v_mfma_f32_32x32x16_bf16 v[80:95], v[116:119], v[152:155], v[80:95]
	v_mfma_f32_32x32x16_bf16 v[96:111], v[10:13], v[152:155], v[96:111]
	ds_read_b128 v[6:9], v14 offset:16384
	ds_read_b128 v[10:13], v14 offset:16896
	ds_read_b128 v[112:115], v14 offset:17408
	ds_read_b128 v[116:119], v14 offset:17920
	s_waitcnt lgkmcnt(4)
	v_mfma_f32_32x32x16_bf16 v[80:95], v[120:123], v[156:159], v[80:95]
	v_mfma_f32_32x32x16_bf16 v[96:111], v[2:5], v[156:159], v[96:111]
	s_waitcnt vmcnt(0)
	s_barrier
	s_add_i32 s3, s68, 3
	s_cmp_lt_u32 s3, s67
	s_cbranch_scc0 .Lyka_ynodma
	s_add_i32 s3, s69, s66
	s_mov_b32 m0, s3
	v_lshl_add_u64 v[120:121], v[168:169], 0, s[28:29]
	global_load_lds_dwordx4 v[168:169], off sc1
	s_add_i32 m0, s3, 0x2000
	s_nop 0
	global_load_lds_dwordx4 v[120:121], off sc1
	v_lshl_add_u64 v[120:121], v[168:169], 0, s[40:41]
	s_add_i32 m0, s3, 0x4000
	s_nop 0
	global_load_lds_dwordx4 v[120:121], off sc1
	v_lshl_add_u64 v[120:121], v[168:169], 0, s[80:81]
	s_add_i32 m0, s3, 0x6000
	s_nop 0
	global_load_lds_dwordx4 v[120:121], off sc1

.LBB0_2152:
	s_cmp_ge_u32 s78, s66
	s_cbranch_scc1 .Lykb_xtail
	v_add_u32_e32 v0, s81, v208
	ds_read_b128 v[80:83], v0
	ds_read_b128 v[84:87], v0 offset:512
	ds_read_b128 v[6:9], v0 offset:2048
	ds_read_b128 v[112:115], v0 offset:2560
	ds_read_b128 v[10:13], v0 offset:4096
	ds_read_b128 v[116:119], v0 offset:4608
	ds_read_b128 v[2:5], v0 offset:6144
	ds_read_b128 v[120:123], v0 offset:6656
	s_and_b64 vcc, exec, s[8:9]
	s_cbranch_vccnz .LBB0_2161
	s_add_i32 s3, s79, s68
	s_mov_b32 m0, s3
	v_lshl_add_u64 v[14:15], v[170:171], 0, s[24:25]
	global_load_lds_dwordx4 v[170:171], off sc1
	s_add_i32 m0, s3, 0x2000
	s_nop 0
	global_load_lds_dwordx4 v[14:15], off sc1
	v_lshl_add_u64 v[14:15], v[170:171], 0, s[26:27]
	s_add_i32 m0, s3, 0x4000
	s_nop 0
	global_load_lds_dwordx4 v[14:15], off sc1
	v_lshl_add_u64 v[14:15], v[170:171], 0, s[44:45]
	s_add_i32 m0, s3, 0x6000
	s_nop 0
	global_load_lds_dwordx4 v[14:15], off sc1

.Lykb_ypre:
	s_cmp_eq_u32 s67, 0
	s_cbranch_scc1 .Lykb_pre
	s_mov_b32 s5, m0
	s_add_i32 s3, s68, 0x10000
	s_mov_b32 m0, s3
	v_lshl_add_u64 v[2:3], v[170:171], 0, s[24:25]
	global_load_lds_dwordx4 v[170:171], off sc1
	s_add_i32 s4, s3, 0x2000
	s_mov_b32 m0, s4
	v_lshl_add_u64 v[4:5], v[170:171], 0, s[26:27]
	global_load_lds_dwordx4 v[2:3], off sc1
	s_add_i32 s4, s3, 0x4000
	s_mov_b32 m0, s4
	v_lshl_add_u64 v[2:3], v[170:171], 0, s[44:45]
	global_load_lds_dwordx4 v[4:5], off sc1
	s_addk_i32 s3, 0x6000
	s_mov_b32 m0, s3
	s_nop 0
	global_load_lds_dwordx4 v[2:3], off sc1
	s_mov_b32 m0, s5

.Lykb_ytop:
	s_cmp_ge_u32 s78, s66
	s_cbranch_scc1 .Lykb_ytail
	v_add_u32_e32 v0, s81, v208
	ds_read_b128 v[80:83], v0
	ds_read_b128 v[84:87], v0 offset:512
	ds_read_b128 v[6:9], v0 offset:2048
	ds_read_b128 v[112:115], v0 offset:2560
	ds_read_b128 v[10:13], v0 offset:4096
	ds_read_b128 v[116:119], v0 offset:4608
	ds_read_b128 v[2:5], v0 offset:6144
	ds_read_b128 v[120:123], v0 offset:6656
	v_add_f32_e32 v14, 0, v168
	v_add_f32_e32 v15, 0, v169
	v_cvt_pk_bf16_f32 v124, v168, v172
	v_add_f32_e32 v14, v172, v14
	v_add_f32_e32 v15, v173, v15
	v_cvt_pk_bf16_f32 v125, v174, v176
	v_add_f32_e32 v14, v174, v14
	v_add_f32_e32 v15, v175, v15
	v_cvt_pk_bf16_f32 v126, v178, v180
	v_add_f32_e32 v14, v176, v14
	v_add_f32_e32 v15, v177, v15
	v_cvt_pk_bf16_f32 v127, v182, v184
	v_add_f32_e32 v14, v178, v14
	v_add_f32_e32 v15, v179, v15
	v_cvt_pk_bf16_f32 v128, v186, v188
	v_add_f32_e32 v14, v180, v14
	v_add_f32_e32 v15, v181, v15
	v_cvt_pk_bf16_f32 v129, v190, v192
	v_add_f32_e32 v14, v182, v14
	v_add_f32_e32 v15, v183, v15
	v_cvt_pk_bf16_f32 v130, v194, v196
	v_add_f32_e32 v14, v184, v14
	v_add_f32_e32 v15, v185, v15
	v_cvt_pk_bf16_f32 v131, v198, v200
	v_add_f32_e32 v14, v186, v14
	v_add_f32_e32 v15, v187, v15
	v_cvt_pk_bf16_f32 v132, v169, v173
	v_add_f32_e32 v14, v188, v14
	v_add_f32_e32 v15, v189, v15
	v_cvt_pk_bf16_f32 v133, v175, v177
	v_add_f32_e32 v14, v190, v14
	v_add_f32_e32 v15, v191, v15
	v_cvt_pk_bf16_f32 v134, v179, v181
	v_add_f32_e32 v14, v192, v14
	v_add_f32_e32 v15, v193, v15
	v_cvt_pk_bf16_f32 v135, v183, v185
	v_add_f32_e32 v14, v194, v14
	v_add_f32_e32 v15, v195, v15
	v_cvt_pk_bf16_f32 v136, v187, v189
	v_add_f32_e32 v14, v196, v14
	v_add_f32_e32 v15, v197, v15
	v_cvt_pk_bf16_f32 v137, v191, v193
	v_add_f32_e32 v14, v198, v14
	v_add_f32_e32 v15, v199, v15
	v_cvt_pk_bf16_f32 v138, v195, v197
	v_add_f32_e32 v14, v200, v14
	v_add_f32_e32 v15, v201, v15
	v_cvt_pk_bf16_f32 v139, v199, v201
	v_add_f32_e32 v0, v14, v15
	s_waitcnt lgkmcnt(7)
	v_mfma_f32_32x32x16_bf16 v[96:111], v[80:83], v[144:147], 0
	v_add_u32_e32 v14, s80, v209
	s_waitcnt lgkmcnt(6)
	v_mfma_f32_32x32x16_bf16 v[80:95], v[84:87], v[144:147], 0
	s_waitcnt lgkmcnt(4)
	v_mfma_f32_32x32x16_bf16 v[80:95], v[112:115], v[148:151], v[80:95]
	v_mfma_f32_32x32x16_bf16 v[96:111], v[6:9], v[148:151], v[96:111]
	s_waitcnt lgkmcnt(2)
	v_mfma_f32_32x32x16_bf16 v[80:95], v[116:119], v[152:155], v[80:95]
	v_mfma_f32_32x32x16_bf16 v[96:111], v[10:13], v[152:155], v[96:111]
	ds_read_b128 v[6:9], v14 offset:16384
	ds_read_b128 v[10:13], v14 offset:16896
	ds_read_b128 v[112:115], v14 offset:17408
	ds_read_b128 v[116:119], v14 offset:17920
	s_waitcnt lgkmcnt(4)
	v_mfma_f32_32x32x16_bf16 v[80:95], v[120:123], v[156:159], v[80:95]
	v_mfma_f32_32x32x16_bf16 v[96:111], v[2:5], v[156:159], v[96:111]
	s_waitcnt vmcnt(0)
	s_barrier
	s_add_i32 s3, s78, 3
	s_cmp_lt_u32 s3, s69
	s_cbranch_scc0 .Lykb_ynodma
	s_add_i32 s3, s79, s68
	s_mov_b32 m0, s3
	v_lshl_add_u64 v[120:121], v[170:171], 0, s[24:25]
	global_load_lds_dwordx4 v[170:171], off sc1
	s_add_i32 m0, s3, 0x2000
	s_nop 0
	global_load_lds_dwordx4 v[120:121], off sc1
	v_lshl_add_u64 v[120:121], v[170:171], 0, s[26:27]
	s_add_i32 m0, s3, 0x4000
	s_nop 0
	global_load_lds_dwordx4 v[120:121], off sc1
	v_lshl_add_u64 v[120:121], v[170:171], 0, s[44:45]
	s_add_i32 m0, s3, 0x6000
	s_nop 0
	global_load_lds_dwordx4 v[120:121], off sc1
